# scan workgroups: dropped the L1 invalidate between the S5 chunk-end GEMM and the scan (same-CU write-through data, never read earlier)
# speedup vs baseline: 1.0059x; 1.0025x over previous
; __device__ __forceinline__ void sincos_rev(float rev, float& s, float& c) { const float f = rev - floorf(rev); s = __builtin_amdgcn_sinf(f); c = __builtin_amdgcn_cosf(f); }
; #define OPAQUE_TID() int tid = threadIdx.x; asm volatile("" : "+v"(tid)); const int lane = tid & 63; const int wave = __builtin_amdgcn_readfirstlane(tid >> 6); (void)lane; (void)wave
; __global__ void __launch_bounds__(NWAVES * 64, 2) mega_fwd(Args args) {
;     ...
;             __builtin_amdgcn_fence(__ATOMIC_ACQUIRE, "agent"); asm volatile("s_waitcnt vmcnt(0)" ::: "memory");
;             OPAQUE_TID();
;             const int p = lane, seg = wave;
; #pragma unroll 1
;             for (int dir = 0; dir < 2; ++dir) {
;             const float lr = args.in[10][(dir * 32 + g) * 64 + p], li = args.in[11][(dir * 32 + g) * 64 + p], delta = expf(args.in[12][dir * 32 + g]);
;             const float mag = expf(16.0f * delta * lr); float sn, cs; { const double rev = 16.0 * (double)delta * (double)li * 0.15915494309189535; sincos_rev((float)(rev - floor(rev)), sn, cs); }
;             const float ar = mag * cs, ai = mag * sn;
;             const float* Eb = EB + ((size_t)(g * 1024 + b * 512)) * 256 + dir * 128 + p;
;             bf16* Ab = AUG + ((size_t)(g * 1024 + b * 512)) * 512 + 256 + dir * 128 + p;
;             float er[64], ei[64];
; #pragma unroll
;             for (int q = 0; q < 64; ++q) { const int sidx = seg * 64 + q, c = dir ? 511 - sidx : sidx; er[q] = Eb[(size_t)c * 256]; ei[q] = Eb[(size_t)c * 256 + 64]; }
.LBB0_677:
	v_writelane_b32 v252, s70, 30
	v_mov_b32_e32 v1, v0
	s_waitcnt vmcnt(0) lgkmcnt(0)
	v_writelane_b32 v252, s71, 31
	v_writelane_b32 v252, s82, 32
	s_waitcnt vmcnt(0)
	v_mov_b32_e32 v2, 0
	v_and_b32_e32 v94, 63, v1
	v_writelane_b32 v252, s83, 33
	v_writelane_b32 v252, s76, 34
	v_readfirstlane_b32 s3, v1
	v_lshlrev_b32_e32 v6, 1, v94
	v_writelane_b32 v252, s77, 35
	v_writelane_b32 v252, s89, 36
	v_writelane_b32 v252, s96, 4
	v_mov_b32_e32 v7, v2
	s_ashr_i32 s2, s3, 6
	v_writelane_b32 v252, s97, 5
	v_writelane_b32 v252, s92, 6
	v_lshl_add_u64 v[6:7], s[0:1], 0, v[6:7]
	s_and_b32 s1, s3, 0xffffffc0
	v_writelane_b32 v252, s93, 7
	v_writelane_b32 v252, s84, 37
	v_lshlrev_b32_e32 v4, 2, v94
	v_mov_b32_e32 v5, v2
	v_writelane_b32 v252, s85, 38
	v_writelane_b32 v252, s86, 39
	s_cmp_gt_i32 s2, 0
	v_writelane_b32 v252, s87, 40
	v_lshl_add_u64 v[4:5], s[4:5], 0, v[4:5]
	s_cselect_b64 s[4:5], -1, 0
	v_writelane_b32 v252, s4, 41
	s_cmp_lt_u32 s3, 64
	s_movk_i32 s0, 0xffc0
	v_writelane_b32 v252, s5, 42
	s_cselect_b64 s[4:5], -1, 0
	v_mov_b32_e32 v3, s3
	v_writelane_b32 v252, s4, 43
	v_bfi_b32 v3, s0, v3, v1
	s_sub_i32 s0, 0x1ff, s1
	v_writelane_b32 v252, s5, 44
	v_writelane_b32 v252, s0, 45
	s_or_b32 s0, s1, 1
	v_writelane_b32 v252, s0, 46
	s_sub_i32 s0, 0x1ff, s0
	v_writelane_b32 v252, s0, 47
	s_or_b32 s0, s1, 2
	v_writelane_b32 v252, s0, 48
	s_sub_i32 s0, 0x1ff, s0
	v_writelane_b32 v252, s0, 49
	s_or_b32 s0, s1, 3
	v_writelane_b32 v252, s0, 50
	s_sub_i32 s0, 0x1ff, s0
	v_writelane_b32 v252, s0, 51
	s_or_b32 s0, s1, 4
	v_writelane_b32 v252, s0, 52
	s_sub_i32 s0, 0x1ff, s0
	v_writelane_b32 v252, s0, 53
	s_or_b32 s0, s1, 5
	v_writelane_b32 v252, s0, 54
	s_sub_i32 s0, 0x1ff, s0
	v_writelane_b32 v252, s0, 55
	s_or_b32 s0, s1, 6
	v_writelane_b32 v252, s0, 56
	s_sub_i32 s0, 0x1ff, s0
	v_writelane_b32 v252, s0, 57
	s_or_b32 s0, s1, 7
	v_writelane_b32 v252, s0, 58
	s_sub_i32 s0, 0x1ff, s0
	v_writelane_b32 v252, s0, 59
	s_or_b32 s0, s1, 8
	v_writelane_b32 v252, s0, 60
	s_sub_i32 s0, 0x1ff, s0
	v_writelane_b32 v252, s0, 61
	s_or_b32 s0, s1, 9
	v_writelane_b32 v252, s0, 62
	s_sub_i32 s0, 0x1ff, s0
	v_writelane_b32 v252, s0, 63
	s_or_b32 s0, s1, 10
	s_or_b32 s3, s3, 63
	v_writelane_b32 v253, s0, 0
	s_sub_i32 s0, 0x1ff, s0
	v_writelane_b32 v253, s0, 1
	s_or_b32 s0, s1, 11
	v_writelane_b32 v253, s0, 2
	s_sub_i32 s0, 0x1ff, s0
	v_writelane_b32 v253, s0, 3
	s_or_b32 s0, s1, 12
	v_writelane_b32 v253, s0, 4
	s_sub_i32 s0, 0x1ff, s0
	v_writelane_b32 v253, s0, 5
	s_or_b32 s0, s1, 13
	v_writelane_b32 v253, s0, 6
	s_sub_i32 s0, 0x1ff, s0
	v_writelane_b32 v253, s0, 7
	s_or_b32 s0, s1, 14
	v_writelane_b32 v253, s0, 8
	s_sub_i32 s0, 0x1ff, s0
	v_writelane_b32 v253, s0, 9
	s_or_b32 s0, s1, 15
	v_writelane_b32 v253, s0, 10
	s_sub_i32 s0, 0x1ff, s0
	v_writelane_b32 v253, s0, 11
	s_or_b32 s0, s1, 16
	v_writelane_b32 v253, s0, 12
	s_sub_i32 s0, 0x1ff, s0
	v_writelane_b32 v253, s0, 13
	s_or_b32 s0, s1, 17
	v_writelane_b32 v253, s0, 14
	s_sub_i32 s0, 0x1ff, s0
	v_writelane_b32 v253, s0, 15
	s_or_b32 s0, s1, 18
	v_writelane_b32 v253, s0, 16
	s_sub_i32 s0, 0x1ff, s0
	v_writelane_b32 v253, s0, 17
	s_or_b32 s0, s1, 19
	v_writelane_b32 v253, s0, 18
	s_sub_i32 s0, 0x1ff, s0
	v_writelane_b32 v253, s0, 19
	s_or_b32 s0, s1, 20
	v_writelane_b32 v253, s0, 20
	s_sub_i32 s0, 0x1ff, s0
	v_writelane_b32 v253, s0, 21
	s_or_b32 s0, s1, 21
	v_writelane_b32 v253, s0, 22
	s_sub_i32 s0, 0x1ff, s0
	v_writelane_b32 v253, s0, 23
	s_or_b32 s0, s1, 22
	v_writelane_b32 v253, s0, 24
	s_sub_i32 s0, 0x1ff, s0
	v_writelane_b32 v253, s0, 25
	s_or_b32 s0, s1, 23
	v_writelane_b32 v253, s0, 26
	s_sub_i32 s0, 0x1ff, s0
	v_writelane_b32 v253, s0, 27
	s_or_b32 s0, s1, 24
	v_writelane_b32 v253, s0, 28
	s_sub_i32 s0, 0x1ff, s0
	v_writelane_b32 v253, s0, 29
	s_or_b32 s0, s1, 25
	v_writelane_b32 v253, s0, 30
	s_sub_i32 s0, 0x1ff, s0
	v_writelane_b32 v253, s0, 31
	s_or_b32 s0, s1, 26
	v_writelane_b32 v253, s0, 32
	s_sub_i32 s0, 0x1ff, s0
	v_writelane_b32 v253, s0, 33
	s_or_b32 s0, s1, 27
	v_writelane_b32 v253, s0, 34
	s_sub_i32 s0, 0x1ff, s0
	v_writelane_b32 v253, s0, 35
	s_or_b32 s0, s1, 28
	v_writelane_b32 v253, s0, 36
	s_sub_i32 s0, 0x1ff, s0
	v_writelane_b32 v253, s0, 37
	s_or_b32 s0, s1, 29
; __device__ __forceinline__ void sincos_rev(float rev, float& s, float& c) { const float f = rev - floorf(rev); s = __builtin_amdgcn_sinf(f); c = __builtin_amdgcn_cosf(f); }
; __global__ void __launch_bounds__(NWAVES * 64, 2) mega_fwd(Args args) {
;     ...
;             const int p = lane, seg = wave;
; #pragma unroll 1
;             for (int dir = 0; dir < 2; ++dir) {
;             const float lr = args.in[10][(dir * 32 + g) * 64 + p], li = args.in[11][(dir * 32 + g) * 64 + p], delta = expf(args.in[12][dir * 32 + g]);
;             const float mag = expf(16.0f * delta * lr); float sn, cs; { const double rev = 16.0 * (double)delta * (double)li * 0.15915494309189535; sincos_rev((float)(rev - floor(rev)), sn, cs); }
;             const float ar = mag * cs, ai = mag * sn;
;             const float* Eb = EB + ((size_t)(g * 1024 + b * 512)) * 256 + dir * 128 + p;
;             bf16* Ab = AUG + ((size_t)(g * 1024 + b * 512)) * 512 + 256 + dir * 128 + p;
;             float er[64], ei[64];
; #pragma unroll
;             for (int q = 0; q < 64; ++q) { const int sidx = seg * 64 + q, c = dir ? 511 - sidx : sidx; er[q] = Eb[(size_t)c * 256]; ei[q] = Eb[(size_t)c * 256 + 64]; }
;             float sr = 0.f, si = 0.f;
; #pragma unroll
;             for (int q = 0; q < 64; ++q) { const float nr = ar * sr - ai * si + er[q], ni = ar * si + ai * sr + ei[q]; sr = nr; si = ni; }
	v_writelane_b32 v253, s0, 38
	s_sub_i32 s0, 0x1ff, s0
	v_writelane_b32 v253, s0, 39
	s_or_b32 s0, s1, 30
	v_writelane_b32 v253, s0, 40
	s_sub_i32 s0, 0x1ff, s0
	v_writelane_b32 v253, s0, 41
	s_or_b32 s0, s1, 31
	v_writelane_b32 v253, s0, 42
	s_sub_i32 s0, 0x1ff, s0
	v_writelane_b32 v253, s0, 43
	s_or_b32 s0, s1, 32
	v_writelane_b32 v253, s0, 44
	s_sub_i32 s0, 0x1ff, s0
	v_writelane_b32 v253, s0, 45
	s_or_b32 s0, s1, 33
	v_writelane_b32 v253, s0, 46
	s_sub_i32 s0, 0x1ff, s0
	v_writelane_b32 v253, s0, 47
	s_or_b32 s0, s1, 34
	v_writelane_b32 v253, s0, 48
	s_sub_i32 s0, 0x1ff, s0
	v_writelane_b32 v253, s0, 49
	s_or_b32 s0, s1, 35
	v_writelane_b32 v253, s0, 50
	s_sub_i32 s0, 0x1ff, s0
	v_writelane_b32 v253, s0, 51
	s_or_b32 s0, s1, 36
	v_writelane_b32 v253, s0, 52
	s_sub_i32 s0, 0x1ff, s0
	v_writelane_b32 v253, s0, 53
	s_or_b32 s0, s1, 37
	v_writelane_b32 v253, s0, 54
	s_sub_i32 s0, 0x1ff, s0
	v_writelane_b32 v253, s0, 55
	s_or_b32 s0, s1, 38
	v_writelane_b32 v253, s0, 56
	s_sub_i32 s0, 0x1ff, s0
	v_writelane_b32 v253, s0, 57
	s_or_b32 s0, s1, 39
	v_writelane_b32 v253, s0, 58
	s_sub_i32 s0, 0x1ff, s0
	v_writelane_b32 v253, s0, 59
	s_or_b32 s0, s1, 40
	v_writelane_b32 v253, s0, 60
	s_sub_i32 s0, 0x1ff, s0
	v_writelane_b32 v253, s0, 61
	s_or_b32 s0, s1, 41
	v_writelane_b32 v253, s0, 62
	s_sub_i32 s0, 0x1ff, s0
	v_writelane_b32 v253, s0, 63
	s_or_b32 s0, s1, 42
	v_writelane_b32 v254, s0, 0
	s_sub_i32 s0, 0x1ff, s0
	v_writelane_b32 v254, s0, 1
	s_or_b32 s0, s1, 43
	v_writelane_b32 v254, s0, 2
	s_sub_i32 s0, 0x1ff, s0
	v_writelane_b32 v254, s0, 3
	s_or_b32 s0, s1, 44
	v_writelane_b32 v254, s0, 4
	s_sub_i32 s0, 0x1ff, s0
	v_writelane_b32 v254, s0, 5
	s_or_b32 s0, s1, 45
	v_writelane_b32 v254, s0, 6
	s_sub_i32 s0, 0x1ff, s0
	v_writelane_b32 v254, s0, 7
	s_or_b32 s0, s1, 46
	v_writelane_b32 v254, s0, 8
	s_sub_i32 s0, 0x1ff, s0
	v_writelane_b32 v254, s0, 9
	s_or_b32 s0, s1, 47
	v_writelane_b32 v254, s0, 10
	s_sub_i32 s0, 0x1ff, s0
	v_writelane_b32 v254, s0, 11
	s_or_b32 s0, s1, 48
	v_writelane_b32 v254, s0, 12
	s_sub_i32 s0, 0x1ff, s0
	v_writelane_b32 v254, s0, 13
	s_or_b32 s0, s1, 49
	v_writelane_b32 v254, s0, 14
	s_sub_i32 s0, 0x1ff, s0
	v_writelane_b32 v254, s0, 15
	s_or_b32 s0, s1, 50
	v_writelane_b32 v254, s0, 16
	s_sub_i32 s0, 0x1ff, s0
	v_writelane_b32 v254, s0, 17
	s_or_b32 s0, s1, 51
	v_writelane_b32 v254, s0, 18
	s_sub_i32 s0, 0x1ff, s0
	v_writelane_b32 v254, s0, 19
	s_or_b32 s0, s1, 52
	v_writelane_b32 v254, s0, 20
	s_sub_i32 s0, 0x1ff, s0
	v_writelane_b32 v254, s0, 21
	s_or_b32 s0, s1, 53
	v_writelane_b32 v254, s0, 22
	s_sub_i32 s0, 0x1ff, s0
	v_writelane_b32 v254, s0, 23
	s_or_b32 s0, s1, 54
	v_writelane_b32 v254, s0, 24
	s_sub_i32 s0, 0x1ff, s0
	v_writelane_b32 v254, s0, 25
	s_or_b32 s0, s1, 55
	v_writelane_b32 v254, s0, 26
	s_sub_i32 s0, 0x1ff, s0
	v_writelane_b32 v254, s0, 27
	s_or_b32 s0, s1, 56
	v_writelane_b32 v254, s0, 28
	s_sub_i32 s0, 0x1ff, s0
	v_writelane_b32 v254, s0, 29
	s_or_b32 s0, s1, 57
	v_writelane_b32 v254, s0, 30
	s_sub_i32 s0, 0x1ff, s0
	v_writelane_b32 v254, s0, 31
	s_or_b32 s0, s1, 58
	v_writelane_b32 v254, s0, 32
	s_sub_i32 s0, 0x1ff, s0
	v_writelane_b32 v254, s0, 33
	s_or_b32 s0, s1, 59
	v_writelane_b32 v254, s0, 34
	s_sub_i32 s0, 0x1ff, s0
	v_writelane_b32 v254, s0, 35
	s_or_b32 s0, s1, 60
	v_writelane_b32 v254, s0, 36
	s_sub_i32 s0, 0x1ff, s0
	v_writelane_b32 v254, s0, 37
	s_or_b32 s0, s1, 61
	v_writelane_b32 v254, s0, 38
	s_sub_i32 s0, 0x1ff, s0
	v_writelane_b32 v254, s0, 39
	v_writelane_b32 v254, s1, 40
	s_or_b32 s0, s1, 62
	v_writelane_b32 v254, s0, 41
	s_sub_i32 s0, 0x1ff, s0
	v_writelane_b32 v254, s0, 42
	v_writelane_b32 v254, s3, 43
	s_sub_i32 s0, 0x1ff, s3
	v_writelane_b32 v254, s0, 44
	s_and_b32 s0, s2, 7
	s_cmp_gt_u32 s2, 7
	s_cselect_b64 s[4:5], -1, 0
	v_writelane_b32 v254, s4, 45
	s_and_b32 s33, s2, 0x7ffffff8
	s_cmp_lg_u32 s0, 0
	v_writelane_b32 v254, s5, 46
	v_writelane_b32 v254, s0, 47
	s_cselect_b64 s[2:3], -1, 0
	v_lshlrev_b32_e32 v3, 3, v3
	v_writelane_b32 v254, s2, 48
	v_lshl_add_u32 v95, v94, 3, 0
	v_mov_b32_e32 v96, 0x7f800000
	v_add_u32_e32 v97, 0, v3
	s_movk_i32 s66, 0x7fff
	s_mov_b32 s0, 0
	s_mov_b64 s[40:41], -1
	v_writelane_b32 v254, s3, 49
	s_branch .LBB0_679
